# v54 with non-leader workgroups polling the cross-XCD release word directly instead of the per-XCD generation
# baseline (speedup 1.0000x reference)
; __device__ __forceinline__ unsigned xb_ld(unsigned* p)              { return __hip_atomic_load(p, __ATOMIC_RELAXED, __HIP_MEMORY_SCOPE_AGENT); }
; __device__ __forceinline__ unsigned xb_add(unsigned* p, unsigned v) { return __hip_atomic_fetch_add(p, v, __ATOMIC_RELAXED, __HIP_MEMORY_SCOPE_AGENT); }
; #define XB_SPIN(cond, bar) do { unsigned _sp = 0; while (cond) { __builtin_amdgcn_s_sleep(1); \
;     if ((++_sp & 255u) == 0u) { if (xb_ld(&(bar)[XB_TMO])) break; if (_sp > XB_SPIN_CAP) { atomicAdd(&(bar)[XB_TMO], 1u); break; } } } } while (0)
; __device__ __forceinline__ void xcd_barrier(const XcdBarrier& b) {
;     ...
;         const unsigned old = xb_add(&bar[XB_XSUB(b.x)], 1u);
;         const unsigned gen = old / nloc;
;         if (old + 1u == (gen + 1u) * nloc) {
;             __builtin_amdgcn_fence(__ATOMIC_RELEASE, "agent");
;             asm volatile("s_waitcnt vmcnt(0)" ::: "memory");
;             const unsigned og = xb_add(&bar[XB_TOP], 1u);
;             const unsigned tg = og / nx;
;             if (og + 1u == (tg + 1u) * nx) xb_add(&bar[XB_TOPGEN], 1u);
;             else XB_SPIN(xb_ld(&bar[XB_TOPGEN]) == tg, bar);
;             __builtin_amdgcn_fence(__ATOMIC_ACQUIRE, "agent");
;             xb_add(&bar[XB_XGEN(b.x)], 1u);
;             asm volatile("s_waitcnt vmcnt(0)" ::: "memory");
;         } else {
;             XB_SPIN(xb_ld(&bar[XB_XGEN(b.x)]) == gen, bar);
;             __builtin_amdgcn_fence(__ATOMIC_ACQUIRE, "agent");
;             asm volatile("s_waitcnt vmcnt(0)" ::: "memory");
.LBB0_849:
	v_readlane_b32 s2, v254, 42
	v_readlane_b32 s3, v254, 43
	v_readlane_b32 s2, v254, 41
	s_mov_b32 s7, s3
	s_lshl_b32 s6, s2, 6
	v_writelane_b32 v254, s2, 42
	v_mov_b32_e32 v1, 0x1000
	v_sub_u32_e32 v4, 0, v2
	v_writelane_b32 v254, s3, 43
	s_lshl_b64 s[2:3], s[6:7], 2
	v_readlane_b32 s6, v252, 2
	v_readlane_b32 s7, v252, 3
	s_add_u32 s6, s6, s2
	s_addc_u32 s7, s7, s3
	s_nop 2
	global_atomic_add v3, v1, v183, s[6:7] offset:1024 sc0
	v_cvt_f32_u32_e32 v1, v2
	v_rcp_iflag_f32_e32 v1, v1
	s_nop 0
	v_mul_f32_e32 v1, 0x4f7ffffe, v1
	v_cvt_u32_f32_e32 v1, v1
	v_mul_lo_u32 v4, v4, v1
	v_mul_hi_u32 v4, v1, v4
	v_add_u32_e32 v1, v1, v4
	s_waitcnt vmcnt(0)
	v_mul_hi_u32 v1, v3, v1
	v_mul_lo_u32 v4, v1, v2
	v_sub_u32_e32 v4, v3, v4
	v_add_u32_e32 v5, 1, v1
	v_cmp_ge_u32_e32 vcc, v4, v2
	v_add_u32_e32 v3, 1, v3
	s_nop 0
	v_cndmask_b32_e32 v1, v1, v5, vcc
	v_sub_u32_e32 v5, v4, v2
	v_cndmask_b32_e32 v4, v4, v5, vcc
	v_add_u32_e32 v5, 1, v1
	v_cmp_ge_u32_e32 vcc, v4, v2
	s_nop 1
	v_cndmask_b32_e32 v1, v1, v5, vcc
	v_mul_lo_u32 v4, v2, v1
	v_add_u32_e32 v2, v4, v2
	v_cmp_ne_u32_e32 vcc, v3, v2
	s_and_saveexec_b64 s[2:3], vcc
	s_xor_b64 s[8:9], exec, s[2:3]
	s_cbranch_execz .LBB0_863
	buffer_inv sc1
	s_waitcnt lgkmcnt(0)
	v_readlane_b32 s12, v254, 6
	v_readlane_b32 s13, v254, 7
	s_nop 4
	global_load_dword v0, v113, s[12:13] sc1
	s_waitcnt vmcnt(0)
	v_cmp_eq_u32_e32 vcc, v0, v1
	s_and_saveexec_b64 s[10:11], vcc
	s_cbranch_execz .LBB0_862
	s_mov_b32 s2, 1
	s_mov_b64 s[14:15], 0
	s_branch .LBB0_853
